# v6 + rewritten weight-conversion item (32 row loads back to back, immediate-offset ds_write, LDS reads up front) + ssd_out[1] conversion moved to the first FFN-up tail
# speedup vs baseline: 1.0508x; 1.0095x over previous
; #define LAS __attribute__((address_space(3)))
; __global__ void __launch_bounds__(NTHREADS, 2) mk_fwd(Args a) {
;     extern __shared__ __attribute__((aligned(16))) unsigned char lds[];
;     unsigned char* ws = a.ws;
;     bf16_t* XB = (bf16_t*)(ws + WS_XB); bf16_t* BIG = (bf16_t*)(ws + WS_BIG); float* RSX = (float*)(ws + WS_RSX); float* SSQP = (float*)(ws + WS_SSQP);
;     volatile LAS unsigned* bst = (volatile LAS unsigned*)((LAS unsigned char*)lds + 131072);
;     if (threadIdx.x == 0) { bst[0] = 0u; bst[1] = 0u; }
;     __syncthreads();
;     (void)xcd_barrier_post((unsigned*)(ws + WS_BAR), bst);
;     const bool fusedres = (FUSE_RESID != 0) && (gridDim.x == 256) && (a.ph_hi - a.ph_lo > 1);
.LBB0_6:
	s_load_dword s27, s[0:1], 0xb8
	s_add_u32 s2, s0, 0xb8
	s_addc_u32 s3, s1, 0
	v_writelane_b32 v253, s2, 12
	s_load_dwordx16 s[36:51], s[0:1], 0x0
	s_waitcnt lgkmcnt(0)
	s_lshl_b32 s101, s27, 3
	s_mov_b32 s100, 0xffff
	s_cmp_lg_u32 s27, 0x100
	s_cbranch_scc1 .Lcv_init_done
	s_mov_b32 s100, 0x105

; __global__ void __launch_bounds__(NTHREADS, 2) mk_fwd(Args a) {
;     ...
;             if (rep == 0) {
;                 unsigned cmask = 0u;
;                 if (s == 0 && li == 0) cmask = (1u << 2) | (1u << 8) | (1u << 12);
;                 else if (s == 5 && li == 0) cmask = (1u << 4) | (1u << 6) | (1u << 9) | (1u << 13);
;                 else if (s == 5 && li == 1) cmask = (1u << 1) | (1u << 3) | (1u << 10) | (1u << 14);
;                 else if (s == 0 && li == 2) cmask = (1u << 5) | (1u << 7) | (1u << 11) | (1u << 15);
;                 if (cmask) {
;                     const int G = (int)gridDim.x, rem = S.nwg % G;
;                     if (rem == 0) convert_weights(a, (float*)lds, cmask, (int)blockIdx.x, G);
;                     else if ((int)blockIdx.x >= rem) convert_weights(a, (float*)lds, cmask, (int)blockIdx.x - rem, G - rem);
;                 }
;             }
.LBB0_281:
	s_waitcnt vmcnt(0)
	v_readlane_b32 s92, v254, 53
	v_readlane_b32 s80, v254, 55
	v_readlane_b32 s88, v254, 57
	v_readlane_b32 s93, v254, 54
	v_readlane_b32 s81, v254, 56
	v_readlane_b32 s89, v254, 58
	s_mov_b32 s26, 0x9300000
	v_readlane_b32 s73, v255, 28
	s_barrier
	s_cmp_lg_u32 s27, 0x100
	s_cbranch_scc1 .LBB0_282
	s_cmp_lt_u32 s92, 0x80
	s_cbranch_scc1 .LBB0_282
	s_mov_b32 s100, 0x11258
	s_cmp_eq_u32 s34, 15
	s_cbranch_scc0 .Lcv_m1
	s_mov_b32 s100, 0x12402

; __device__ __forceinline__ unsigned pk2(float lo, float hi) { unsigned r; asm volatile("v_cvt_pk_bf16_f32 %0, %1, %2" : "=v"(r) : "v"(lo), "v"(hi)); return r; }
; __device__ __forceinline__ void p0_transpose_item(const float* W, int K, int N, bf16_t* WT, const float* ks, float* scr, int item, int lane, int ilv) {
;     ...
;     const int c = lane & 7;
;     float sc[8];
; #pragma unroll
;     for (int q = 0; q < 8; ++q) sc[q] = ks ? ks[k0 + 8 * c + q] : 1.0f;
; #pragma unroll
;     for (int jj = 0; jj < 4; ++jj) { const int n = (lane >> 3) + 8 * jj; const float* s = scr + (8 * c) * 33 + n;
;         uint4 o; o.x = pk2(s[0 * 33] * sc[0], s[1 * 33] * sc[1]); o.y = pk2(s[2 * 33] * sc[2], s[3 * 33] * sc[3]); o.z = pk2(s[4 * 33] * sc[4], s[5 * 33] * sc[5]); o.w = pk2(s[6 * 33] * sc[6], s[7 * 33] * sc[7]);
;         *(uint4*)(WT + (size_t)(d0 + n) * K + k0 + 8 * c) = o; }
;     __builtin_amdgcn_fence(__ATOMIC_RELEASE, "wavefront"); __builtin_amdgcn_wave_barrier();
.LBB0_505:
	ds_read2_b32 v[92:93], v52 offset1:33
	ds_read2_b32 v[94:95], v52 offset0:66 offset1:99
	ds_read2_b32 v[96:97], v52 offset0:132 offset1:165
	ds_read2_b32 v[98:99], v52 offset0:198 offset1:231
	ds_read2_b32 v[100:101], v52 offset0:8 offset1:41
	ds_read2_b32 v[102:103], v52 offset0:74 offset1:107
	ds_read2_b32 v[104:105], v52 offset0:140 offset1:173
	ds_read2_b32 v[106:107], v52 offset0:206 offset1:239
	ds_read2_b32 v[108:109], v52 offset0:16 offset1:49
	ds_read2_b32 v[110:111], v52 offset0:82 offset1:115
	ds_read2_b32 v[112:113], v52 offset0:148 offset1:181
	ds_read2_b32 v[114:115], v52 offset0:214 offset1:247
	ds_read2_b32 v[116:117], v52 offset0:24 offset1:57
	ds_read2_b32 v[118:119], v52 offset0:90 offset1:123
	ds_read2_b32 v[120:121], v52 offset0:156 offset1:189
	ds_read2_b32 v[122:123], v52 offset0:222 offset1:255
	v_ashrrev_i32_e32 v19, 31, v18
	v_lshl_add_u64 v[34:35], v[18:19], 1, v[16:17]
	v_add_u32_e32 v36, v58, v23
	v_mad_u64_u32 v[36:37], s[82:83], v36, s3, 0
	v_lshl_add_u64 v[48:49], v[36:37], 1, v[34:35]
	v_add_u32_e32 v36, v58, v53
	v_mad_u64_u32 v[36:37], s[82:83], v36, s3, 0
	v_lshl_add_u64 v[50:51], v[36:37], 1, v[34:35]
	v_add_u32_e32 v36, v58, v54
	v_mad_u64_u32 v[36:37], s[82:83], v36, s3, 0
	v_lshl_add_u64 v[26:27], v[36:37], 1, v[34:35]
	v_add_u32_e32 v36, v58, v55
	v_mad_u64_u32 v[36:37], s[82:83], v36, s3, 0
	v_lshl_add_u64 v[28:29], v[36:37], 1, v[34:35]
	s_waitcnt lgkmcnt(12)
	v_mul_f32_e32 v92, v40, v92
	v_mul_f32_e32 v93, v41, v93
	v_mul_f32_e32 v94, v42, v94
	v_mul_f32_e32 v95, v43, v95
	v_mul_f32_e32 v96, v44, v96
	v_mul_f32_e32 v97, v45, v97
	v_mul_f32_e32 v98, v46, v98
	v_mul_f32_e32 v99, v47, v99
	v_cvt_pk_bf16_f32 v92, v92, v93
	v_cvt_pk_bf16_f32 v93, v94, v95
	v_cvt_pk_bf16_f32 v94, v96, v97
	v_cvt_pk_bf16_f32 v95, v98, v99
	global_store_dwordx4 v[48:49], v[92:95], off
	s_waitcnt lgkmcnt(8)
	v_mul_f32_e32 v100, v40, v100
	v_mul_f32_e32 v101, v41, v101
	v_mul_f32_e32 v102, v42, v102
	v_mul_f32_e32 v103, v43, v103
	v_mul_f32_e32 v104, v44, v104
	v_mul_f32_e32 v105, v45, v105
	v_mul_f32_e32 v106, v46, v106
	v_mul_f32_e32 v107, v47, v107
	v_cvt_pk_bf16_f32 v100, v100, v101
	v_cvt_pk_bf16_f32 v101, v102, v103
	v_cvt_pk_bf16_f32 v102, v104, v105
	v_cvt_pk_bf16_f32 v103, v106, v107
	global_store_dwordx4 v[50:51], v[100:103], off
	s_waitcnt lgkmcnt(4)
	v_mul_f32_e32 v108, v40, v108
	v_mul_f32_e32 v109, v41, v109
	v_mul_f32_e32 v110, v42, v110
	v_mul_f32_e32 v111, v43, v111
	v_mul_f32_e32 v112, v44, v112
	v_mul_f32_e32 v113, v45, v113
	v_mul_f32_e32 v114, v46, v114
	v_mul_f32_e32 v115, v47, v115
	v_cvt_pk_bf16_f32 v108, v108, v109
	v_cvt_pk_bf16_f32 v109, v110, v111
	v_cvt_pk_bf16_f32 v110, v112, v113
	v_cvt_pk_bf16_f32 v111, v114, v115
	global_store_dwordx4 v[26:27], v[108:111], off
	s_waitcnt lgkmcnt(0)
	v_mul_f32_e32 v116, v40, v116
	v_mul_f32_e32 v117, v41, v117
	v_mul_f32_e32 v118, v42, v118
	v_mul_f32_e32 v119, v43, v119
	v_mul_f32_e32 v120, v44, v120
	v_mul_f32_e32 v121, v45, v121
	v_mul_f32_e32 v122, v46, v122
	v_mul_f32_e32 v123, v47, v123
	v_cvt_pk_bf16_f32 v116, v116, v117
	v_cvt_pk_bf16_f32 v117, v118, v119
	v_cvt_pk_bf16_f32 v118, v120, v121
	v_cvt_pk_bf16_f32 v119, v122, v123
	global_store_dwordx4 v[28:29], v[116:119], off
	v_add_u32_e32 v57, s101, v57
	v_cmp_le_i32_e32 vcc, s16, v57
	s_nop 1
	s_or_b64 s[8:9], vcc, s[8:9]
	s_andn2_b64 exec, exec, s[8:9]
	s_cbranch_execz .LBB0_483

; __device__ __forceinline__ void p0_transpose_item(const float* W, int K, int N, bf16_t* WT, const float* ks, float* scr, int item, int lane, int ilv) {
;     const int nblk = N / 32, kb = item / nblk, nb = item % nblk, k0 = 64 * kb, n0 = 32 * nb;
;     const int d0 = ilv == 0 ? n0 : ilv == 1 ? (n0 < FH ? 256 * (n0 / 128) + (n0 % 128) : 256 * ((n0 - FH) / 128) + 128 + ((n0 - FH) % 128))
;                  : (n0 < 1024 ? 2048 + n0 : n0 < 2048 ? 256 * ((n0 - 1024) / 128) + ((n0 - 1024) % 128) : 256 * ((n0 - 2048) / 128) + 128 + ((n0 - 2048) % 128));
; #pragma unroll 8
;     for (int i = 0; i < 32; ++i) { const int kk = 2 * i + (lane >> 5); scr[kk * 33 + (lane & 31)] = W[(size_t)(k0 + kk) * N + n0 + (lane & 31)]; }
;     __builtin_amdgcn_fence(__ATOMIC_RELEASE, "wavefront"); __builtin_amdgcn_wave_barrier();
;     const int c = lane & 7;
;     float sc[8];
; #pragma unroll
;     for (int q = 0; q < 8; ++q) sc[q] = ks ? ks[k0 + 8 * c + q] : 1.0f;
.LBB0_523:
	v_lshlrev_b32_e32 v18, 6, v5
	v_ashrrev_i32_e32 v21, 31, v20
	v_lshl_add_u64 v[20:21], v[20:21], 2, v[14:15]
	v_or_b32_e32 v19, v1, v18
	v_mad_u64_u32 v[24:25], s[82:83], s18, v19, 0
	s_lshl_b32 s0, s18, 3
	s_mov_b32 s1, 0
	v_mad_u32_u24 v59, v1, s79, v10
	v_lshl_add_u64 v[24:25], v[24:25], 2, v[20:21]
	v_mov_b32_e32 v40, 1.0
	v_mov_b32_e32 v41, 1.0
	v_mov_b32_e32 v42, 1.0
	v_mov_b32_e32 v43, 1.0
	v_mov_b32_e32 v44, 1.0
	v_mov_b32_e32 v45, 1.0
	v_mov_b32_e32 v46, 1.0
	v_mov_b32_e32 v47, 1.0
	s_andn2_b64 vcc, exec, s[10:11]
	s_cbranch_vccnz .Lcv_noks
	v_or_b32_e32 v26, v18, v12
	v_ashrrev_i32_e32 v27, 31, v26
	v_lshl_add_u64 v[26:27], v[26:27], 2, s[4:5]
	global_load_dwordx4 v[40:43], v[26:27], off
	global_load_dwordx4 v[44:47], v[26:27], off offset:16
.Lcv_noks:
	global_load_dword v60, v[24:25], off
	v_lshl_add_u64 v[24:25], v[24:25], 0, s[0:1]
	global_load_dword v61, v[24:25], off
	v_lshl_add_u64 v[24:25], v[24:25], 0, s[0:1]
	global_load_dword v62, v[24:25], off
	v_lshl_add_u64 v[24:25], v[24:25], 0, s[0:1]
	global_load_dword v63, v[24:25], off
	v_lshl_add_u64 v[24:25], v[24:25], 0, s[0:1]
	global_load_dword v64, v[24:25], off
	v_lshl_add_u64 v[24:25], v[24:25], 0, s[0:1]
	global_load_dword v65, v[24:25], off
	v_lshl_add_u64 v[24:25], v[24:25], 0, s[0:1]
	global_load_dword v66, v[24:25], off
	v_lshl_add_u64 v[24:25], v[24:25], 0, s[0:1]
	global_load_dword v67, v[24:25], off
	v_lshl_add_u64 v[24:25], v[24:25], 0, s[0:1]
	global_load_dword v68, v[24:25], off
	v_lshl_add_u64 v[24:25], v[24:25], 0, s[0:1]
	global_load_dword v69, v[24:25], off
	v_lshl_add_u64 v[24:25], v[24:25], 0, s[0:1]
	global_load_dword v70, v[24:25], off
	v_lshl_add_u64 v[24:25], v[24:25], 0, s[0:1]
	global_load_dword v71, v[24:25], off
	v_lshl_add_u64 v[24:25], v[24:25], 0, s[0:1]
	global_load_dword v72, v[24:25], off
	v_lshl_add_u64 v[24:25], v[24:25], 0, s[0:1]
	global_load_dword v73, v[24:25], off
	v_lshl_add_u64 v[24:25], v[24:25], 0, s[0:1]
	global_load_dword v74, v[24:25], off
	v_lshl_add_u64 v[24:25], v[24:25], 0, s[0:1]
	global_load_dword v75, v[24:25], off
	v_lshl_add_u64 v[24:25], v[24:25], 0, s[0:1]
	global_load_dword v76, v[24:25], off
	v_lshl_add_u64 v[24:25], v[24:25], 0, s[0:1]
	global_load_dword v77, v[24:25], off
	v_lshl_add_u64 v[24:25], v[24:25], 0, s[0:1]
	global_load_dword v78, v[24:25], off
	v_lshl_add_u64 v[24:25], v[24:25], 0, s[0:1]
	global_load_dword v79, v[24:25], off
	v_lshl_add_u64 v[24:25], v[24:25], 0, s[0:1]
	global_load_dword v80, v[24:25], off
	v_lshl_add_u64 v[24:25], v[24:25], 0, s[0:1]
	global_load_dword v81, v[24:25], off
	v_lshl_add_u64 v[24:25], v[24:25], 0, s[0:1]
	global_load_dword v82, v[24:25], off
	v_lshl_add_u64 v[24:25], v[24:25], 0, s[0:1]
	global_load_dword v83, v[24:25], off
	v_lshl_add_u64 v[24:25], v[24:25], 0, s[0:1]
	global_load_dword v84, v[24:25], off
	v_lshl_add_u64 v[24:25], v[24:25], 0, s[0:1]
	global_load_dword v85, v[24:25], off
	v_lshl_add_u64 v[24:25], v[24:25], 0, s[0:1]
	global_load_dword v86, v[24:25], off
	v_lshl_add_u64 v[24:25], v[24:25], 0, s[0:1]
	global_load_dword v87, v[24:25], off
	v_lshl_add_u64 v[24:25], v[24:25], 0, s[0:1]
	global_load_dword v88, v[24:25], off
	v_lshl_add_u64 v[24:25], v[24:25], 0, s[0:1]
	global_load_dword v89, v[24:25], off
	v_lshl_add_u64 v[24:25], v[24:25], 0, s[0:1]
	global_load_dword v90, v[24:25], off
	v_lshl_add_u64 v[24:25], v[24:25], 0, s[0:1]
	global_load_dword v91, v[24:25], off
	s_waitcnt vmcnt(31)
	ds_write_b32 v59, v60
	s_waitcnt vmcnt(30)
	ds_write_b32 v59, v61 offset:264
	s_waitcnt vmcnt(29)
	ds_write_b32 v59, v62 offset:528
	s_waitcnt vmcnt(28)
	ds_write_b32 v59, v63 offset:792
	s_waitcnt vmcnt(27)
	ds_write_b32 v59, v64 offset:1056
	s_waitcnt vmcnt(26)
	ds_write_b32 v59, v65 offset:1320
	s_waitcnt vmcnt(25)
	ds_write_b32 v59, v66 offset:1584
	s_waitcnt vmcnt(24)
	ds_write_b32 v59, v67 offset:1848
	s_waitcnt vmcnt(23)
	ds_write_b32 v59, v68 offset:2112
	s_waitcnt vmcnt(22)
	ds_write_b32 v59, v69 offset:2376
	s_waitcnt vmcnt(21)
	ds_write_b32 v59, v70 offset:2640
	s_waitcnt vmcnt(20)
	ds_write_b32 v59, v71 offset:2904
	s_waitcnt vmcnt(19)
	ds_write_b32 v59, v72 offset:3168
	s_waitcnt vmcnt(18)
	ds_write_b32 v59, v73 offset:3432
	s_waitcnt vmcnt(17)
	ds_write_b32 v59, v74 offset:3696
	s_waitcnt vmcnt(16)
	ds_write_b32 v59, v75 offset:3960
	s_waitcnt vmcnt(15)
	ds_write_b32 v59, v76 offset:4224
	s_waitcnt vmcnt(14)
	ds_write_b32 v59, v77 offset:4488
	s_waitcnt vmcnt(13)
	ds_write_b32 v59, v78 offset:4752
	s_waitcnt vmcnt(12)
	ds_write_b32 v59, v79 offset:5016
	s_waitcnt vmcnt(11)
	ds_write_b32 v59, v80 offset:5280
	s_waitcnt vmcnt(10)
	ds_write_b32 v59, v81 offset:5544
	s_waitcnt vmcnt(9)
	ds_write_b32 v59, v82 offset:5808
	s_waitcnt vmcnt(8)
	ds_write_b32 v59, v83 offset:6072
	s_waitcnt vmcnt(7)
	ds_write_b32 v59, v84 offset:6336
	s_waitcnt vmcnt(6)
	ds_write_b32 v59, v85 offset:6600
	s_waitcnt vmcnt(5)
	ds_write_b32 v59, v86 offset:6864
	s_waitcnt vmcnt(4)
	ds_write_b32 v59, v87 offset:7128
	s_waitcnt vmcnt(3)
	ds_write_b32 v59, v88 offset:7392
	s_waitcnt vmcnt(2)
	ds_write_b32 v59, v89 offset:7656
	s_waitcnt vmcnt(1)
	ds_write_b32 v59, v90 offset:7920
	s_waitcnt vmcnt(0)
	ds_write_b32 v59, v91 offset:8184
	s_branch .LBB0_505
